# ret_out: v^T tile staged through LDS as well (on top of s_prev and k)
# speedup vs baseline: 1.0159x; 1.0017x over previous
.LBB0_913:
	s_or_b64 exec, exec, s[0:1]
	v_readlane_b32 s20, v253, 13
	v_readlane_b32 s21, v253, 14
	v_ashrrev_i32_e32 v201, 31, v10
	v_mov_b32_e32 v200, v10
	v_lshlrev_b64 v[200:201], 15, v[200:201]
	v_lshlrev_b32_e32 v202, 4, v172
	v_mov_b32_e32 v203, 0
	v_lshl_add_u64 v[200:201], s[20:21], 0, v[200:201]
	v_lshl_add_u64 v[232:233], v[200:201], 0, v[202:203]
	s_mov_b64 s[20:21], 0x1000
	global_load_dwordx4 v[200:203], v[232:233], off
	v_lshl_add_u64 v[232:233], v[232:233], 0, s[20:21]
	global_load_dwordx4 v[204:207], v[232:233], off
	v_lshl_add_u64 v[232:233], v[232:233], 0, s[20:21]
	global_load_dwordx4 v[208:211], v[232:233], off
	v_lshl_add_u64 v[232:233], v[232:233], 0, s[20:21]
	global_load_dwordx4 v[212:215], v[232:233], off
	v_lshl_add_u64 v[232:233], v[232:233], 0, s[20:21]
	global_load_dwordx4 v[216:219], v[232:233], off
	v_lshl_add_u64 v[232:233], v[232:233], 0, s[20:21]
	global_load_dwordx4 v[220:223], v[232:233], off
	v_lshl_add_u64 v[232:233], v[232:233], 0, s[20:21]
	global_load_dwordx4 v[224:227], v[232:233], off
	v_lshl_add_u64 v[232:233], v[232:233], 0, s[20:21]
	global_load_dwordx4 v[228:231], v[232:233], off
	v_and_b32_e32 v169, 3, v2
	v_cvt_f32_ubyte0_e32 v0, v169
	v_sub_f32_e32 v0, 0xc0a00000, v0
	v_cmp_gt_f32_e32 vcc, s34, v0
	s_mov_b32 s0, 0x3f2aaaab
	v_and_b32_e32 v113, 31, v172
	v_cndmask_b32_e32 v2, 0, v187, vcc
	v_add_f32_e32 v0, v0, v2
	v_exp_f32_e32 v0, v0
	v_cndmask_b32_e32 v2, 0, v188, vcc
	v_ashrrev_i32_e32 v191, 1, v172
	v_and_or_b32 v193, v191, 32, v113
	v_ldexp_f32 v11, v0, v2
	v_sub_f32_e32 v0, 1.0, v11
	v_add_f32_e32 v2, -1.0, v0
	v_sub_f32_e32 v3, v2, v0
	v_add_f32_e32 v3, 1.0, v3
	v_sub_f32_e64 v2, -v11, v2
	v_add_f32_e32 v4, v2, v3
	v_frexp_mant_f32_e32 v5, v0
	v_cvt_f64_f32_e32 v[2:3], v0
	v_frexp_exp_i32_f64_e32 v2, v[2:3]
	v_cmp_gt_f32_e32 vcc, s0, v5
	v_readlane_b32 s0, v252, 55
	v_readlane_b32 s1, v252, 56
	v_subbrev_co_u32_e32 v111, vcc, 0, v2, vcc
	v_sub_u32_e32 v2, 0, v111
	v_ldexp_f32 v0, v0, v2
	v_ldexp_f32 v2, v4, v2
	v_add_f32_e32 v4, -1.0, v0
	v_add_f32_e32 v3, 1.0, v4
	v_sub_f32_e32 v3, v0, v3
	v_add_f32_e32 v5, v2, v3
	v_add_f32_e32 v3, 1.0, v0
	v_add_f32_e32 v6, -1.0, v3
	v_sub_f32_e32 v0, v0, v6
	v_add_f32_e32 v0, v2, v0
	v_add_f32_e32 v114, v3, v0
	v_rcp_f32_e32 v116, v114
	v_sub_f32_e32 v2, v114, v3
	v_add_f32_e32 v3, v4, v5
	v_sub_f32_e32 v115, v0, v2
	v_mul_f32_e32 v117, v3, v116
	v_mul_f32_e32 v18, v114, v117
	v_sub_f32_e32 v0, v3, v4
	v_fma_f32 v4, v117, v114, -v18
	v_fmac_f32_e32 v4, v117, v115
	v_add_f32_e32 v2, v18, v4
	v_sub_f32_e32 v19, v3, v2
	v_sub_f32_e32 v0, v5, v0
	v_pk_add_f32 v[6:7], v[2:3], v[18:19] neg_lo:[0,1] neg_hi:[0,1]
	v_mov_b32_e32 v5, v2
	v_pk_add_f32 v[2:3], v[6:7], v[4:5] neg_lo:[0,1] neg_hi:[0,1]
	v_bfe_u32 v173, v172, 5, 1
	v_add_f32_e32 v0, v0, v3
	v_add_f32_e32 v18, v2, v0
	v_add_u32_e32 v2, v112, v193
	v_ashrrev_i32_e32 v3, 31, v2
	v_lshlrev_b64 v[174:175], 10, v[2:3]
	v_lshl_add_u64 v[2:3], s[0:1], 0, v[174:175]
	v_lshlrev_b32_e32 v0, 8, v169
	v_lshl_add_u64 v[2:3], v[2:3], 0, v[0:1]
	v_lshlrev_b32_e32 v32, 4, v173
	v_mov_b32_e32 v33, v1
	v_lshl_add_u64 v[2:3], v[2:3], 0, v[32:33]
	global_load_dwordx4 v[78:81], v[2:3], off
	global_load_dwordx4 v[74:77], v[2:3], off offset:32
	global_load_dwordx4 v[70:73], v[2:3], off offset:64
	global_load_dwordx4 v[66:69], v[2:3], off offset:96
	global_load_dwordx4 v[62:65], v[2:3], off offset:128
	global_load_dwordx4 v[58:61], v[2:3], off offset:160
	global_load_dwordx4 v[54:57], v[2:3], off offset:192
	global_load_dwordx4 v[50:53], v[2:3], off offset:224
	v_add_u32_e32 v2, v112, v113
	v_ashrrev_i32_e32 v3, 31, v2
	v_readlane_b32 s20, v252, 53
	v_lshlrev_b64 v[2:3], 10, v[2:3]
	v_readlane_b32 s21, v252, 54
	v_and_b32_e32 v192, 0xffffffc0, v191
	v_lshlrev_b32_e32 v16, 1, v16
	v_mov_b32_e32 v17, v1
	v_lshlrev_b32_e32 v20, 3, v173
	v_mov_b32_e32 v21, v1
	v_lshl_add_u64 v[2:3], s[20:21], 0, v[2:3]
	v_or_b32_e32 v110, v192, v113
	v_lshl_add_u64 v[12:13], v[12:13], 0, v[16:17]
	v_mov_b64_e32 v[248:249], v[12:13]
	v_lshl_add_u64 v[2:3], v[2:3], 0, v[0:1]
	v_lshl_add_u64 v[12:13], v[12:13], 0, v[20:21]
	v_mad_i64_i32 v[16:17], s[0:1], v14, v110, 0
	v_lshl_add_u64 v[22:23], v[2:3], 0, v[32:33]
	v_lshl_add_u64 v[16:17], v[16:17], 1, v[12:13]
	v_lshrrev_b32_e32 v232, 4, v172
	v_add_u32_e32 v232, v112, v232
	v_ashrrev_i32_e32 v233, 31, v232
	v_lshlrev_b64 v[232:233], 10, v[232:233]
	v_and_b32_e32 v254, 15, v172
	v_lshlrev_b32_e32 v254, 4, v254
	v_mov_b32_e32 v255, 0
	v_lshl_add_u64 v[232:233], s[20:21], 0, v[232:233]
	v_lshl_add_u64 v[232:233], v[232:233], 0, v[0:1]
	v_lshl_add_u64 v[232:233], v[232:233], 0, v[254:255]
	s_mov_b64 s[20:21], 0x4000
	global_load_dwordx4 v[46:49], v[232:233], off
	v_lshl_add_u64 v[232:233], v[232:233], 0, s[20:21]
	global_load_dwordx4 v[42:45], v[232:233], off
	v_lshl_add_u64 v[232:233], v[232:233], 0, s[20:21]
	global_load_dwordx4 v[38:41], v[232:233], off
	v_lshl_add_u64 v[232:233], v[232:233], 0, s[20:21]
	global_load_dwordx4 v[28:31], v[232:233], off
	v_mul_u32_u24_e32 v242, 0x90, v110
	v_add3_u32 v242, v242, v20, v182
	v_add_u32_e32 v242, 0xd400, v242
	v_add_u32_e32 v243, 0x1200, v242
	v_lshrrev_b32_e32 v246, 3, v172
	v_mad_i64_i32 v[244:245], s[0:1], v14, v246, 0
	v_and_b32_e32 v246, 7, v172
	v_lshlrev_b32_e32 v246, 4, v246
	v_mov_b32_e32 v247, 0
	v_lshl_add_u64 v[244:245], v[244:245], 1, v[248:249]
	v_lshl_add_u64 v[244:245], v[244:245], 0, v[246:247]
	v_lshlrev_b32_e32 v246, 6, v14
	global_load_dwordx4 v[94:97], v[244:245], off
	v_lshl_add_u64 v[244:245], v[244:245], 0, v[246:247]
	global_load_dwordx4 v[90:93], v[244:245], off
	v_lshl_add_u64 v[244:245], v[244:245], 0, v[246:247]
	global_load_dwordx4 v[86:89], v[244:245], off
	v_lshl_add_u64 v[244:245], v[244:245], 0, v[246:247]
	global_load_dwordx4 v[82:85], v[244:245], off
	v_add_f32_e32 v15, v19, v18
	v_mul_f32_e32 v118, v116, v15
	v_mul_f32_e32 v12, v114, v118
	v_fma_f32 v16, v118, v114, -v12
	v_fmac_f32_e32 v16, v118, v115
	v_sub_f32_e32 v13, v19, v15
	v_add_f32_e32 v14, v12, v16
	v_add_f32_e32 v20, v18, v13
	v_sub_f32_e32 v13, v15, v14
	v_pk_add_f32 v[18:19], v[14:15], v[12:13] neg_lo:[0,1] neg_hi:[0,1]
	v_mov_b32_e32 v17, v14
	v_pk_add_f32 v[14:15], v[18:19], v[16:17] neg_lo:[0,1] neg_hi:[0,1]
	s_mov_b32 s0, 0x3f317218
	v_add_f32_e32 v12, v20, v15
	v_add_f32_e32 v12, v14, v12
	v_add_f32_e32 v12, v13, v12
	v_add_f32_e32 v13, v117, v118
	v_sub_f32_e32 v14, v13, v117
	v_mul_f32_e32 v12, v116, v12
	v_sub_f32_e32 v14, v118, v14
	v_add_f32_e32 v14, v14, v12
	v_add_f32_e32 v16, v13, v14
	v_mul_f32_e32 v17, v16, v16
	v_fmamk_f32 v12, v17, 0x3e9b6dac, v185
	v_fmaak_f32 v171, v17, v12, 0x3f2aaada
	v_cvt_f32_i32_e32 v12, v111
	v_sub_f32_e32 v13, v16, v13
	v_sub_f32_e32 v13, v14, v13
	v_ldexp_f32 v18, v13, 1
	v_mul_f32_e32 v13, v16, v17
	v_ldexp_f32 v15, v16, 1
	v_pk_mul_f32 v[16:17], v[12:13], v[170:171]
	v_cmp_nlt_f32_e32 vcc, 1.0, v11
	v_fma_f32 v14, v12, s0, -v16
	v_fmac_f32_e32 v14, 0xb102e308, v12
	v_pk_add_f32 v[12:13], v[16:17], v[14:15]
	s_mov_b32 s0, 0x33800000
	v_sub_f32_e32 v15, v13, v15
	v_sub_f32_e32 v15, v17, v15
	v_add_f32_e32 v19, v18, v15
	v_mov_b32_e32 v18, v16
	v_pk_add_f32 v[16:17], v[12:13], v[16:17] neg_lo:[0,1] neg_hi:[0,1]
	v_pk_add_f32 v[20:21], v[12:13], v[18:19]
	v_mov_b32_e32 v15, v12
	v_mov_b32_e32 v17, v21
	v_pk_add_f32 v[22:23], v[14:15], v[16:17] neg_lo:[0,1] neg_hi:[0,1]
	v_pk_add_f32 v[14:15], v[14:15], v[16:17]
	v_mov_b32_e32 v18, v19
	v_pk_add_f32 v[16:17], v[14:15], v[12:13] op_sel:[1,0] op_sel_hi:[0,1] neg_lo:[0,1] neg_hi:[0,1]
	v_pk_add_f32 v[114:115], v[20:21], v[16:17] op_sel_hi:[1,0] neg_lo:[0,1] neg_hi:[0,1]
	v_mov_b32_e32 v20, v21
	v_mov_b32_e32 v21, v15
	v_pk_mov_b32 v[16:17], v[12:13], v[16:17] op_sel:[1,0]
	v_mov_b32_e32 v19, v12
	v_pk_add_f32 v[16:17], v[20:21], v[16:17] neg_lo:[0,1] neg_hi:[0,1]
	v_mov_b32_e32 v114, v22
	v_pk_add_f32 v[12:13], v[18:19], v[16:17] neg_lo:[0,1] neg_hi:[0,1]
	v_mov_b32_e32 v23, v15
	v_pk_add_f32 v[16:17], v[114:115], v[12:13]
	v_lshlrev_b32_e32 v171, 2, v173
	v_pk_add_f32 v[18:19], v[16:17], v[16:17] op_sel:[0,1] op_sel_hi:[1,0]
	v_ashrrev_i32_e32 v111, 31, v110
	v_pk_add_f32 v[14:15], v[14:15], v[18:19] op_sel:[1,0] op_sel_hi:[0,1]
	v_mov_b32_e32 v17, v14
	v_pk_add_f32 v[20:21], v[16:17], v[22:23] neg_lo:[0,1] neg_hi:[0,1]
	v_mov_b32_e32 v13, v18
	v_sub_f32_e32 v15, v16, v20
	v_pk_add_f32 v[12:13], v[12:13], v[20:21] neg_lo:[0,1] neg_hi:[0,1]
	v_sub_f32_e32 v15, v22, v15
	v_add_f32_e32 v12, v12, v15
	v_add_f32_e32 v12, v12, v13
	v_add_f32_e32 v12, v14, v12
	v_cndmask_b32_e32 v12, v189, v12, vcc
	v_cmp_neq_f32_e32 vcc, 1.0, v11
	s_nop 1
	v_cndmask_b32_e32 v12, v190, v12, vcc
	v_cmp_gt_f32_e32 vcc, s0, v11
	v_readlane_b32 s0, v253, 13
	v_readlane_b32 s1, v253, 14
	v_cndmask_b32_e64 v11, v12, -v11, vcc
	v_mul_f32_e32 v194, 0x3fb8aa3b, v11
	v_ashrrev_i32_e32 v11, 31, v10
	v_lshlrev_b64 v[10:11], 15, v[10:11]
	v_lshl_add_u64 v[154:155], s[0:1], 0, v[10:11]
	s_waitcnt vmcnt(0)
	v_lshrrev_b32_e32 v232, 4, v172
	v_and_b32_e32 v233, 15, v172
	v_mul_u32_u24_e32 v232, 0x110, v232
	v_lshl_add_u32 v232, v233, 4, v232
	v_add_u32_e32 v232, v232, v182
	v_mul_u32_u24_e32 v241, 0x110, v113
	v_add3_u32 v241, v241, v32, v182
	v_add_u32_e32 v232, 0x9000, v232
	v_add_u32_e32 v241, 0x9000, v241
	ds_write_b128 v232, v[46:49]
	ds_write_b128 v232, v[42:45] offset:4352
	ds_write_b128 v232, v[38:41] offset:8704
	ds_write_b128 v232, v[28:31] offset:13056
	v_lshrrev_b32_e32 v233, 3, v172
	v_and_b32_e32 v244, 7, v172
	v_mul_u32_u24_e32 v233, 0x90, v233
	v_lshl_add_u32 v233, v244, 4, v233
	v_add_u32_e32 v233, v233, v182
	v_add_u32_e32 v233, 0xd400, v233
	ds_write_b128 v233, v[94:97]
	ds_write_b128 v233, v[90:93] offset:4608
	ds_write_b128 v233, v[86:89] offset:9216
	ds_write_b128 v233, v[82:85] offset:13824
	s_waitcnt lgkmcnt(0)
	s_barrier
	ds_read_b128 v[6:9], v241
	ds_read_b128 v[46:49], v241 offset:32
	ds_read_b128 v[42:45], v241 offset:64
	ds_read_b128 v[38:41], v241 offset:96
	ds_read_b128 v[28:31], v241 offset:128
	ds_read_b128 v[2:5], v241 offset:160
	ds_read_b128 v[24:27], v241 offset:192
	ds_read_b128 v[150:153], v241 offset:224
	s_waitcnt lgkmcnt(0)
	v_mfma_f32_32x32x16_bf16 v[8:23], v[6:9], v[78:81], 0
	v_or_b32_e32 v195, 32, v113
	v_lshlrev_b64 v[6:7], 8, v[110:111]
	v_lshl_add_u64 v[6:7], v[154:155], 0, v[6:7]
	v_lshl_add_u64 v[6:7], v[6:7], 0, v[32:33]
	s_nop 0
	v_mfma_f32_32x32x16_bf16 v[8:23], v[46:49], v[74:77], v[8:23]
	s_nop 0
	v_mfma_f32_32x32x16_bf16 v[8:23], v[42:45], v[70:73], v[8:23]
	s_nop 0
	v_mfma_f32_32x32x16_bf16 v[8:23], v[38:41], v[66:69], v[8:23]
	s_nop 0
	v_mfma_f32_32x32x16_bf16 v[8:23], v[28:31], v[62:65], v[8:23]
	v_add_u32_e32 v28, v112, v195
	v_ashrrev_i32_e32 v29, 31, v28
	v_lshlrev_b64 v[28:29], 10, v[28:29]
	v_lshl_add_u64 v[28:29], s[20:21], 0, v[28:29]
	v_lshl_add_u64 v[28:29], v[28:29], 0, v[0:1]
	v_lshl_add_u64 v[28:29], v[28:29], 0, v[32:33]
	s_nop 0
	v_mfma_f32_32x32x16_bf16 v[8:23], v[2:5], v[58:61], v[8:23]
	ds_read_b128 v[2:5], v241 offset:8704
	ds_read_b128 v[146:149], v241 offset:8736
	ds_read_b128 v[142:145], v241 offset:8768
	ds_read_b128 v[138:141], v241 offset:8800
	ds_read_b128 v[130:133], v241 offset:8832
	ds_read_b128 v[126:129], v241 offset:8864
	ds_read_b128 v[134:137], v241 offset:8896
	s_nop 0
	ds_read_b128 v[28:31], v241 offset:8928
	s_nop 0
	v_mfma_f32_32x32x16_bf16 v[8:23], v[24:27], v[54:57], v[8:23]
	s_waitcnt vmcnt(16)
	v_lshrrev_b32_e32 v232, 4, v172
	v_and_b32_e32 v233, 15, v172
	v_mul_u32_u24_e32 v232, 0x110, v232
	v_lshl_add_u32 v232, v233, 4, v232
	v_add_u32_e32 v232, v232, v182
	v_mul_u32_u24_e32 v233, 0x110, v110
	v_add3_u32 v233, v233, v32, v182
	v_add_u32_e32 v232, 0x800, v232
	v_add_u32_e32 v233, 0x800, v233
	ds_write_b128 v232, v[200:203]
	ds_write_b128 v232, v[204:207] offset:4352
	ds_write_b128 v232, v[208:211] offset:8704
	ds_write_b128 v232, v[212:215] offset:13056
	ds_write_b128 v232, v[216:219] offset:17408
	ds_write_b128 v232, v[220:223] offset:21760
	ds_write_b128 v232, v[224:227] offset:26112
	ds_write_b128 v232, v[228:231] offset:30464
	s_waitcnt lgkmcnt(0)
	s_barrier
	ds_read_b128 v[24:27], v233
	ds_read_b128 v[122:125], v233 offset:32
	ds_read_b128 v[118:121], v233 offset:64
	ds_read_b128 v[114:117], v233 offset:96
	ds_read_b128 v[110:113], v233 offset:128
	ds_read_b128 v[46:49], v233 offset:160
	ds_read_b128 v[42:45], v233 offset:192
	ds_read_b128 v[38:41], v233 offset:224
	s_nop 0
	v_mfma_f32_32x32x16_bf16 v[8:23], v[150:153], v[50:53], v[8:23]
	v_min_u32_e32 v0, v171, v193
	v_max_u32_e32 v6, v171, v193
	v_sub_u32_e32 v0, v6, v0
	v_cvt_f32_u32_e32 v0, v0
	v_or_b32_e32 v6, 1, v171
	v_mul_f32_e32 v7, v194, v0
	v_cmp_gt_f32_e32 vcc, s34, v7
	s_nop 1
	v_cndmask_b32_e32 v7, 0, v187, vcc
	v_fmac_f32_e32 v7, v194, v0
	v_exp_f32_e32 v0, v7
	v_min_u32_e32 v7, v6, v193
	v_max_u32_e32 v6, v6, v193
	v_sub_u32_e32 v6, v6, v7
	v_cvt_f32_u32_e32 v7, v6
	v_cndmask_b32_e32 v6, 0, v188, vcc
	v_ldexp_f32 v6, v0, v6
	v_mul_f32_e32 v0, v194, v7
	v_cmp_gt_f32_e32 vcc, s34, v0
	s_nop 1
	v_cndmask_b32_e32 v0, 0, v187, vcc
	v_fmac_f32_e32 v0, v194, v7
	v_exp_f32_e32 v0, v0
	v_or_b32_e32 v7, 2, v171
	v_min_u32_e32 v150, v7, v193
	v_max_u32_e32 v7, v7, v193
	v_sub_u32_e32 v7, v7, v150
	v_cvt_f32_u32_e32 v152, v7
	v_cndmask_b32_e32 v7, 0, v188, vcc
	v_ldexp_f32 v7, v0, v7
	v_pk_mul_f32 v[150:151], v[8:9], v[6:7]
	v_or_b32_e32 v6, 3, v171
	v_min_u32_e32 v7, v6, v193
	v_max_u32_e32 v6, v6, v193
	v_sub_u32_e32 v6, v6, v7
	v_cvt_f32_u32_e32 v6, v6
	v_mul_f32_e32 v0, v194, v152
	v_cmp_gt_f32_e32 vcc, s34, v0
	v_mul_f32_e32 v8, v194, v6
	s_nop 0
	v_cndmask_b32_e32 v0, 0, v187, vcc
	v_cndmask_b32_e32 v7, 0, v188, vcc
	v_cmp_gt_f32_e32 vcc, s34, v8
	v_fmac_f32_e32 v0, v194, v152
	v_exp_f32_e32 v0, v0
	v_cndmask_b32_e32 v8, 0, v187, vcc
	v_fmac_f32_e32 v8, v194, v6
	v_or_b32_e32 v6, 8, v171
	v_min_u32_e32 v9, v6, v193
	v_max_u32_e32 v6, v6, v193
	v_sub_u32_e32 v6, v6, v9
	v_exp_f32_e32 v8, v8
	v_cvt_f32_u32_e32 v9, v6
	v_ldexp_f32 v6, v0, v7
	v_cndmask_b32_e32 v0, 0, v188, vcc
	v_ldexp_f32 v7, v8, v0
	v_mul_f32_e32 v0, v194, v9
	v_cmp_gt_f32_e32 vcc, s34, v0
	v_or_b32_e32 v8, 9, v171
	v_pk_mul_f32 v[152:153], v[10:11], v[6:7]
	v_cndmask_b32_e32 v0, 0, v187, vcc
	v_fmac_f32_e32 v0, v194, v9
	v_min_u32_e32 v9, v8, v193
	v_max_u32_e32 v8, v8, v193
	v_sub_u32_e32 v8, v8, v9
	v_exp_f32_e32 v0, v0
	v_cvt_f32_u32_e32 v8, v8
	v_cndmask_b32_e32 v6, 0, v188, vcc
	v_or_b32_e32 v7, 10, v171
	v_ldexp_f32 v6, v0, v6
	v_mul_f32_e32 v0, v194, v8
	v_cmp_gt_f32_e32 vcc, s34, v0
	s_nop 1
	v_cndmask_b32_e32 v0, 0, v187, vcc
	v_fmac_f32_e32 v0, v194, v8
	v_exp_f32_e32 v0, v0
	v_min_u32_e32 v8, v7, v193
	v_max_u32_e32 v7, v7, v193
	v_sub_u32_e32 v7, v7, v8
	v_cvt_f32_u32_e32 v8, v7
	v_cndmask_b32_e32 v7, 0, v188, vcc
	v_ldexp_f32 v7, v0, v7
	v_pk_mul_f32 v[156:157], v[12:13], v[6:7]
	v_or_b32_e32 v6, 11, v171
	v_min_u32_e32 v7, v6, v193
	v_max_u32_e32 v6, v6, v193
	v_sub_u32_e32 v6, v6, v7
	v_cvt_f32_u32_e32 v6, v6
	v_mul_f32_e32 v0, v194, v8
	v_cmp_gt_f32_e32 vcc, s34, v0
	s_nop 1
	v_cndmask_b32_e32 v0, 0, v187, vcc
	v_fmac_f32_e32 v0, v194, v8
	v_mul_f32_e32 v8, v194, v6
	v_cndmask_b32_e32 v7, 0, v188, vcc
	v_cmp_gt_f32_e32 vcc, s34, v8
	v_exp_f32_e32 v0, v0
	s_nop 0
	v_cndmask_b32_e32 v8, 0, v187, vcc
	v_fmac_f32_e32 v8, v194, v6
	v_or_b32_e32 v6, 16, v171
	v_min_u32_e32 v9, v6, v193
	v_max_u32_e32 v6, v6, v193
	v_sub_u32_e32 v6, v6, v9
	v_exp_f32_e32 v8, v8
	v_cvt_f32_u32_e32 v9, v6
	v_ldexp_f32 v6, v0, v7
	v_cndmask_b32_e32 v0, 0, v188, vcc
	v_ldexp_f32 v7, v8, v0
	v_mul_f32_e32 v0, v194, v9
	v_cmp_gt_f32_e32 vcc, s34, v0
	v_or_b32_e32 v8, 17, v171
	v_pk_mul_f32 v[158:159], v[14:15], v[6:7]
	v_cndmask_b32_e32 v0, 0, v187, vcc
	v_fmac_f32_e32 v0, v194, v9
	v_min_u32_e32 v9, v8, v193
	v_max_u32_e32 v8, v8, v193
	v_sub_u32_e32 v8, v8, v9
	v_exp_f32_e32 v0, v0
	v_cvt_f32_u32_e32 v8, v8
	v_cndmask_b32_e32 v6, 0, v188, vcc
	v_or_b32_e32 v7, 18, v171
	v_ldexp_f32 v6, v0, v6
	v_mul_f32_e32 v0, v194, v8
	v_cmp_gt_f32_e32 vcc, s34, v0
	s_nop 1
	v_cndmask_b32_e32 v0, 0, v187, vcc
	v_fmac_f32_e32 v0, v194, v8
	v_exp_f32_e32 v0, v0
	v_min_u32_e32 v8, v7, v193
	v_max_u32_e32 v7, v7, v193
	v_sub_u32_e32 v7, v7, v8
	v_cvt_f32_u32_e32 v8, v7
	v_cndmask_b32_e32 v7, 0, v188, vcc
	v_ldexp_f32 v7, v0, v7
	v_pk_mul_f32 v[160:161], v[16:17], v[6:7]
	v_or_b32_e32 v6, 19, v171
	v_min_u32_e32 v7, v6, v193
	v_max_u32_e32 v6, v6, v193
	v_sub_u32_e32 v6, v6, v7
	v_cvt_f32_u32_e32 v6, v6
	v_mul_f32_e32 v0, v194, v8
	v_cmp_gt_f32_e32 vcc, s34, v0
	s_nop 1
	v_cndmask_b32_e32 v0, 0, v187, vcc
	v_fmac_f32_e32 v0, v194, v8
	v_mul_f32_e32 v8, v194, v6
	v_cndmask_b32_e32 v7, 0, v188, vcc
	v_cmp_gt_f32_e32 vcc, s34, v8
	v_exp_f32_e32 v0, v0
	s_nop 0
	v_cndmask_b32_e32 v8, 0, v187, vcc
	v_fmac_f32_e32 v8, v194, v6
	v_exp_f32_e32 v6, v8
	v_or_b32_e32 v8, 24, v171
	v_min_u32_e32 v9, v8, v193
	v_max_u32_e32 v8, v8, v193
	v_sub_u32_e32 v8, v8, v9
	v_cvt_f32_u32_e32 v8, v8
	v_ldexp_f32 v176, v0, v7
	v_cndmask_b32_e32 v0, 0, v188, vcc
	v_ldexp_f32 v177, v6, v0
	v_mul_f32_e32 v0, v194, v8
	v_cmp_gt_f32_e32 vcc, s34, v0
	v_or_b32_e32 v6, 25, v171
	v_min_u32_e32 v7, v6, v193
	v_cndmask_b32_e32 v0, 0, v187, vcc
	v_max_u32_e32 v6, v6, v193
	v_fmac_f32_e32 v0, v194, v8
	v_sub_u32_e32 v178, v6, v7
	s_nop 0
	v_mfma_f32_32x32x16_bf16 v[2:17], v[2:5], v[78:81], 0
	v_exp_f32_e32 v0, v0
	v_cvt_f32_u32_e32 v178, v178
	v_pk_mul_f32 v[18:19], v[18:19], v[176:177]
	v_cndmask_b32_e32 v176, 0, v188, vcc
	v_ldexp_f32 v176, v0, v176
	v_mul_f32_e32 v0, v194, v178
	v_cmp_gt_f32_e32 vcc, s34, v0
	s_nop 0
	v_mfma_f32_32x32x16_bf16 v[2:17], v[146:149], v[74:77], v[2:17]
	v_or_b32_e32 v146, 26, v171
	v_cndmask_b32_e32 v0, 0, v187, vcc
	v_fmac_f32_e32 v0, v194, v178
	v_exp_f32_e32 v0, v0
	v_min_u32_e32 v147, v146, v193
	v_max_u32_e32 v146, v146, v193
	v_sub_u32_e32 v146, v146, v147
	s_nop 0
	v_mfma_f32_32x32x16_bf16 v[2:17], v[142:145], v[70:73], v[2:17]
	v_cndmask_b32_e32 v142, 0, v188, vcc
	v_ldexp_f32 v177, v0, v142
	v_or_b32_e32 v142, 27, v171
	v_min_u32_e32 v143, v142, v193
	v_max_u32_e32 v142, v142, v193
	v_cvt_f32_u32_e32 v146, v146
	v_pk_mul_f32 v[20:21], v[20:21], v[176:177]
	s_nop 0
	v_mfma_f32_32x32x16_bf16 v[2:17], v[138:141], v[66:69], v[2:17]
	v_sub_u32_e32 v138, v142, v143
	v_cvt_f32_u32_e32 v138, v138
	v_mul_f32_e32 v0, v194, v146
	v_cmp_gt_f32_e32 vcc, s34, v0
	v_mul_f32_e32 v139, v194, v138
	s_nop 0
	v_cndmask_b32_e32 v0, 0, v187, vcc
	s_nop 0
	v_mfma_f32_32x32x16_bf16 v[2:17], v[130:133], v[62:65], v[2:17]
	v_cmp_gt_f32_e64 s[0:1], s34, v139
	v_fmac_f32_e32 v0, v194, v146
	v_exp_f32_e32 v0, v0
	v_cndmask_b32_e64 v130, 0, v187, s[0:1]
	v_fmac_f32_e32 v130, v194, v138
	v_exp_f32_e32 v131, v130
	v_cndmask_b32_e32 v130, 0, v188, vcc
	v_ldexp_f32 v130, v0, v130
	v_cndmask_b32_e64 v0, 0, v188, s[0:1]
	v_ldexp_f32 v131, v131, v0
	v_or_b32_e32 v0, 32, v171
	s_nop 0
	v_mfma_f32_32x32x16_bf16 v[2:17], v[126:129], v[58:61], v[2:17]
	v_cvt_pk_bf16_f32 v127, v18, v19
	v_min_u32_e32 v18, v0, v193
	v_max_u32_e32 v0, v0, v193
	v_sub_u32_e32 v0, v0, v18
	v_cvt_f32_u32_e32 v0, v0
	v_or_b32_e32 v19, 33, v171
	v_cvt_pk_bf16_f32 v128, v20, v21
	v_min_u32_e32 v20, v19, v193
	v_max_u32_e32 v19, v19, v193
	v_sub_u32_e32 v19, v19, v20
	v_cvt_f32_u32_e32 v19, v19
	v_mul_f32_e32 v18, v194, v0
	v_cmp_gt_f32_e32 vcc, s34, v18
	s_nop 0
	v_mfma_f32_32x32x16_bf16 v[2:17], v[134:137], v[54:57], v[2:17]
	v_mul_f32_e32 v20, v194, v19
	v_cndmask_b32_e32 v18, 0, v187, vcc
	v_fmac_f32_e32 v18, v194, v0
	v_exp_f32_e32 v0, v18
	v_cndmask_b32_e32 v18, 0, v188, vcc
	v_cmp_gt_f32_e32 vcc, s34, v20
	v_pk_mul_f32 v[22:23], v[22:23], v[130:131]
	v_ldexp_f32 v18, v0, v18
	v_cndmask_b32_e32 v20, 0, v187, vcc
	v_fmac_f32_e32 v20, v194, v19
	v_exp_f32_e32 v19, v20
	v_or_b32_e32 v20, 34, v171
	v_min_u32_e32 v21, v20, v193
	v_max_u32_e32 v20, v20, v193
	v_sub_u32_e32 v20, v20, v21
	v_cvt_f32_u32_e32 v20, v20
	v_cndmask_b32_e32 v0, 0, v188, vcc
	v_ldexp_f32 v19, v19, v0
	ds_read2_b64 v[34:37], v242 offset1:2
	ds_read2_b64 v[106:109], v242 offset0:4 offset1:6
	ds_read2_b64 v[102:105], v242 offset0:8 offset1:10
	ds_read2_b64 v[98:101], v242 offset0:12 offset1:14
	ds_read2_b64 v[94:97], v243 offset1:2
	ds_read2_b64 v[90:93], v243 offset0:4 offset1:6
	ds_read2_b64 v[86:89], v243 offset0:8 offset1:10
	ds_read2_b64 v[82:85], v243 offset0:12 offset1:14
	v_mfma_f32_32x32x16_bf16 v[2:17], v[28:31], v[50:53], v[2:17]
	v_mul_f32_e32 v0, v194, v20
	v_cmp_gt_f32_e32 vcc, s34, v0
	v_cvt_pk_bf16_f32 v129, v22, v23
	v_cvt_pk_bf16_f32 v130, v150, v151
	v_cndmask_b32_e32 v0, 0, v187, vcc
	v_fmac_f32_e32 v0, v194, v20
	v_or_b32_e32 v20, 35, v171
	v_min_u32_e32 v21, v20, v193
	v_max_u32_e32 v20, v20, v193
	v_sub_u32_e32 v20, v20, v21
	v_exp_f32_e32 v0, v0
	v_cvt_f32_u32_e32 v20, v20
	v_pk_mul_f32 v[176:177], v[2:3], v[18:19]
	v_cndmask_b32_e32 v2, 0, v188, vcc
	v_ldexp_f32 v2, v0, v2
	v_mul_f32_e32 v0, v194, v20
	v_cmp_gt_f32_e32 vcc, s34, v0
	v_or_b32_e32 v3, 40, v171
	v_min_u32_e32 v18, v3, v193
	v_cndmask_b32_e32 v0, 0, v187, vcc
	v_fmac_f32_e32 v0, v194, v20
	v_exp_f32_e32 v0, v0
	v_max_u32_e32 v3, v3, v193
	v_sub_u32_e32 v3, v3, v18
	v_cvt_f32_u32_e32 v18, v3
	v_cndmask_b32_e32 v3, 0, v188, vcc
	v_ldexp_f32 v3, v0, v3
	v_pk_mul_f32 v[178:179], v[4:5], v[2:3]
	v_or_b32_e32 v2, 41, v171
	v_min_u32_e32 v3, v2, v193
	v_max_u32_e32 v2, v2, v193
	v_sub_u32_e32 v2, v2, v3
	v_cvt_f32_u32_e32 v2, v2
	v_mul_f32_e32 v0, v194, v18
	v_cmp_gt_f32_e32 vcc, s34, v0
	v_cvt_pk_bf16_f32 v131, v152, v153
	v_mul_f32_e32 v4, v194, v2
	v_cndmask_b32_e32 v0, 0, v187, vcc
	v_cndmask_b32_e32 v3, 0, v188, vcc
	v_cmp_gt_f32_e32 vcc, s34, v4
	v_fmac_f32_e32 v0, v194, v18
	v_exp_f32_e32 v0, v0
	v_cndmask_b32_e32 v4, 0, v187, vcc
	v_fmac_f32_e32 v4, v194, v2
	v_or_b32_e32 v2, 42, v171
	v_min_u32_e32 v5, v2, v193
	v_max_u32_e32 v2, v2, v193
	v_sub_u32_e32 v2, v2, v5
	v_exp_f32_e32 v4, v4
	v_cvt_f32_u32_e32 v5, v2
	v_ldexp_f32 v2, v0, v3
	v_cndmask_b32_e32 v0, 0, v188, vcc
	v_ldexp_f32 v3, v4, v0
	v_mul_f32_e32 v0, v194, v5
	v_cmp_gt_f32_e32 vcc, s34, v0
	v_or_b32_e32 v4, 43, v171
	v_pk_mul_f32 v[6:7], v[6:7], v[2:3]
	v_cndmask_b32_e32 v0, 0, v187, vcc
	v_fmac_f32_e32 v0, v194, v5
	v_min_u32_e32 v5, v4, v193
	v_max_u32_e32 v4, v4, v193
	v_sub_u32_e32 v4, v4, v5
	v_exp_f32_e32 v0, v0
	v_cvt_f32_u32_e32 v4, v4
	v_cndmask_b32_e32 v2, 0, v188, vcc
	v_or_b32_e32 v3, 48, v171
	v_ldexp_f32 v2, v0, v2
	v_mul_f32_e32 v0, v194, v4
	v_cmp_gt_f32_e32 vcc, s34, v0
	v_cvt_pk_bf16_f32 v132, v156, v157
	v_cvt_pk_bf16_f32 v133, v158, v159
	v_cndmask_b32_e32 v0, 0, v187, vcc
	v_fmac_f32_e32 v0, v194, v4
	v_exp_f32_e32 v0, v0
	v_min_u32_e32 v4, v3, v193
	v_max_u32_e32 v3, v3, v193
	v_sub_u32_e32 v3, v3, v4
	v_cvt_f32_u32_e32 v4, v3
	v_cndmask_b32_e32 v3, 0, v188, vcc
	v_ldexp_f32 v3, v0, v3
	v_pk_mul_f32 v[8:9], v[8:9], v[2:3]
	v_or_b32_e32 v2, 49, v171
	v_min_u32_e32 v3, v2, v193
	v_max_u32_e32 v2, v2, v193
	v_sub_u32_e32 v2, v2, v3
	v_cvt_f32_u32_e32 v2, v2
	v_mul_f32_e32 v0, v194, v4
	v_cmp_gt_f32_e32 vcc, s34, v0
	v_cvt_pk_bf16_f32 v126, v160, v161
	s_nop 0
	v_cndmask_b32_e32 v0, 0, v187, vcc
	v_fmac_f32_e32 v0, v194, v4
	v_mul_f32_e32 v4, v194, v2
	v_cndmask_b32_e32 v3, 0, v188, vcc
	v_cmp_gt_f32_e32 vcc, s34, v4
	v_exp_f32_e32 v0, v0
	s_nop 0
	v_cndmask_b32_e32 v4, 0, v187, vcc
	v_fmac_f32_e32 v4, v194, v2
	v_or_b32_e32 v2, 50, v171
	v_min_u32_e32 v5, v2, v193
	v_max_u32_e32 v2, v2, v193
	v_sub_u32_e32 v2, v2, v5
	v_exp_f32_e32 v4, v4
	v_cvt_f32_u32_e32 v5, v2
	v_ldexp_f32 v2, v0, v3
	v_cndmask_b32_e32 v0, 0, v188, vcc
	v_ldexp_f32 v3, v4, v0
	v_mul_f32_e32 v0, v194, v5
	v_cmp_gt_f32_e32 vcc, s34, v0
	v_or_b32_e32 v4, 51, v171
	v_pk_mul_f32 v[10:11], v[10:11], v[2:3]
	v_cndmask_b32_e32 v0, 0, v187, vcc
	v_fmac_f32_e32 v0, v194, v5
	v_exp_f32_e32 v0, v0
	v_min_u32_e32 v5, v4, v193
	v_max_u32_e32 v4, v4, v193
	v_cndmask_b32_e32 v2, 0, v188, vcc
	v_sub_u32_e32 v4, v4, v5
	v_ldexp_f32 v18, v0, v2
	v_or_b32_e32 v2, 56, v171
	v_cvt_f32_u32_e32 v4, v4
	v_min_u32_e32 v3, v2, v193
	v_max_u32_e32 v2, v2, v193
	v_sub_u32_e32 v2, v2, v3
	v_cvt_f32_u32_e32 v22, v2
	v_or_b32_e32 v2, v192, v195
	v_ashrrev_i32_e32 v3, 31, v2
	v_mul_f32_e32 v0, v194, v4
	v_lshlrev_b64 v[2:3], 8, v[2:3]
	v_cmp_gt_f32_e32 vcc, s34, v0
	v_lshl_add_u64 v[2:3], v[154:155], 0, v[2:3]
	v_lshl_add_u64 v[20:21], v[2:3], 0, v[32:33]
	v_cndmask_b32_e32 v0, 0, v187, vcc
	v_fmac_f32_e32 v0, v194, v4
	ds_read_b128 v[2:5], v233 offset:8704
	ds_read_b128 v[158:161], v233 offset:8736
	ds_read_b128 v[154:157], v233 offset:8768
	ds_read_b128 v[150:153], v233 offset:8800
	ds_read_b128 v[146:149], v233 offset:8832
	ds_read_b128 v[142:145], v233 offset:8864
	ds_read_b128 v[138:141], v233 offset:8896
	ds_read_b128 v[134:137], v233 offset:8928
	v_exp_f32_e32 v0, v0
	v_cndmask_b32_e32 v19, 0, v188, vcc
	v_ldexp_f32 v19, v0, v19
	v_mul_f32_e32 v0, v194, v22
	v_cmp_gt_f32_e32 vcc, s34, v0
	v_pk_mul_f32 v[12:13], v[12:13], v[18:19]
	v_or_b32_e32 v18, 57, v171
	v_cndmask_b32_e32 v0, 0, v187, vcc
	v_fmac_f32_e32 v0, v194, v22
	v_exp_f32_e32 v0, v0
	v_min_u32_e32 v19, v18, v193
	v_max_u32_e32 v18, v18, v193
	v_sub_u32_e32 v18, v18, v19
	v_cvt_f32_u32_e32 v195, v18
	v_cndmask_b32_e32 v18, 0, v188, vcc
	v_ldexp_f32 v196, v0, v18
	s_waitcnt lgkmcnt(8)
	v_mfma_f32_32x32x16_bf16 v[18:33], v[24:27], v[78:81], 0
	v_mul_f32_e32 v0, v194, v195
	v_cmp_gt_f32_e32 vcc, s34, v0
	s_nop 1
	v_cndmask_b32_e32 v0, 0, v187, vcc
	v_fmac_f32_e32 v0, v194, v195
	v_or_b32_e32 v195, 58, v171
	s_nop 0
	v_mfma_f32_32x32x16_bf16 v[18:33], v[122:125], v[74:77], v[18:33]
	v_min_u32_e32 v197, v195, v193
	v_max_u32_e32 v122, v195, v193
	v_sub_u32_e32 v122, v122, v197
	v_exp_f32_e32 v0, v0
	v_cvt_f32_u32_e32 v122, v122
	v_cndmask_b32_e32 v123, 0, v188, vcc
	v_ldexp_f32 v197, v0, v123
	s_nop 0
	v_mfma_f32_32x32x16_bf16 v[18:33], v[118:121], v[70:73], v[18:33]
	v_or_b32_e32 v118, 59, v171
	v_min_u32_e32 v119, v118, v193
	v_max_u32_e32 v118, v118, v193
	v_sub_u32_e32 v118, v118, v119
	v_cvt_f32_u32_e32 v118, v118
	v_mul_f32_e32 v0, v194, v122
	v_cmp_gt_f32_e32 vcc, s34, v0
	s_nop 0
	v_mfma_f32_32x32x16_bf16 v[18:33], v[114:117], v[66:69], v[18:33]
	v_mul_f32_e32 v114, v194, v118
	v_cndmask_b32_e32 v0, 0, v187, vcc
	v_cmp_gt_f32_e64 s[0:1], s34, v114
	v_fmac_f32_e32 v0, v194, v122
	v_exp_f32_e32 v0, v0
	v_cndmask_b32_e64 v114, 0, v187, s[0:1]
	v_fmac_f32_e32 v114, v194, v118
	s_nop 0
	v_mfma_f32_32x32x16_bf16 v[18:33], v[110:113], v[62:65], v[18:33]
	v_exp_f32_e32 v114, v114
	v_cndmask_b32_e32 v110, 0, v188, vcc
	v_ldexp_f32 v110, v0, v110
	v_cndmask_b32_e64 v0, 0, v188, s[0:1]
	v_ldexp_f32 v111, v114, v0
	v_add_u32_e32 v0, 1, v193
	v_cvt_f32_u32_e32 v0, v0
	s_nop 0
	v_mfma_f32_32x32x16_bf16 v[18:33], v[46:49], v[58:61], v[18:33]
	v_cvt_pk_bf16_f32 v116, v6, v7
	v_mul_f32_e64 v14, v14, v196
	v_mul_f32_e64 v15, v15, v197
	v_mul_f32_e32 v6, v194, v0
	v_cmp_gt_f32_e32 vcc, s34, v6
	v_pk_mul_f32 v[16:17], v[16:17], v[110:111]
	v_cvt_pk_bf16_f32 v114, v176, v177
	v_cndmask_b32_e32 v6, 0, v187, vcc
	s_nop 0
	v_mfma_f32_32x32x16_bf16 v[18:33], v[42:45], v[54:57], v[18:33]
	v_fmac_f32_e32 v6, v194, v0
	v_exp_f32_e32 v0, v6
	v_cndmask_b32_e32 v6, 0, v188, vcc
	v_cvt_pk_bf16_f32 v115, v178, v179
	v_cvt_pk_bf16_f32 v117, v8, v9
	v_ldexp_f32 v0, v0, v6
	v_cvt_pk_bf16_f32 v110, v10, v11
	s_nop 0
	v_mfma_f32_32x32x16_bf16 v[18:33], v[38:41], v[50:53], v[18:33]
	v_cvt_pk_bf16_f32 v111, v12, v13
	v_cvt_pk_bf16_f32 v112, v14, v15
	v_cvt_pk_bf16_f32 v113, v16, v17
	s_waitcnt lgkmcnt(7)
	v_mfma_f32_32x32x16_bf16 v[2:17], v[2:5], v[78:81], 0
	s_movk_i32 s0, 0xffe0
	v_cmp_eq_u32_e32 vcc, 0, v173
	s_barrier
	s_waitcnt lgkmcnt(6)
	v_mfma_f32_32x32x16_bf16 v[2:17], v[158:161], v[74:77], v[2:17]
	s_waitcnt lgkmcnt(5)
	v_mfma_f32_32x32x16_bf16 v[2:17], v[154:157], v[70:73], v[2:17]
	s_waitcnt lgkmcnt(4)
	v_mfma_f32_32x32x16_bf16 v[2:17], v[150:153], v[66:69], v[2:17]
	s_waitcnt lgkmcnt(3)
	v_mfma_f32_32x32x16_bf16 v[2:17], v[146:149], v[62:65], v[2:17]
	s_waitcnt lgkmcnt(2)
	v_mfma_f32_32x32x16_bf16 v[2:17], v[142:145], v[58:61], v[2:17]
	s_waitcnt lgkmcnt(1)
	v_mfma_f32_32x32x16_bf16 v[2:17], v[138:141], v[54:57], v[2:17]
	v_mfma_f32_32x32x16_bf16 v[34:49], v[34:37], v[130:133], 0
	s_waitcnt lgkmcnt(0)
	v_mfma_f32_32x32x16_bf16 v[2:17], v[134:137], v[50:53], v[2:17]
	v_mfma_f32_32x32x16_bf16 v[50:65], v[94:97], v[130:133], 0
	v_mfma_f32_32x32x16_bf16 v[34:49], v[106:109], v[126:129], v[34:49]
	v_mfma_f32_32x32x16_bf16 v[50:65], v[90:93], v[126:129], v[50:65]
	v_mfma_f32_32x32x16_bf16 v[34:49], v[102:105], v[114:117], v[34:49]
	v_mfma_f32_32x32x16_bf16 v[50:65], v[86:89], v[114:117], v[50:65]
	v_mfma_f32_32x32x16_bf16 v[34:49], v[98:101], v[110:113], v[34:49]
	v_mfma_f32_32x32x16_bf16 v[50:65], v[82:85], v[110:113], v[50:65]
	s_nop 10
	v_fma_f32 v66, v0, v18, v34
	v_fma_f32 v67, v0, v19, v35
	v_fma_f32 v68, v0, v20, v36
	v_fma_f32 v69, v0, v21, v37
	v_fma_f32 v70, v0, v22, v38
	v_fma_f32 v71, v0, v23, v39
	v_pk_fma_f32 v[38:39], v[0:1], v[24:25], v[40:41] op_sel_hi:[0,1,1]
	v_pk_fma_f32 v[24:25], v[0:1], v[30:31], v[46:47] op_sel_hi:[0,1,1]
	v_pk_mul_f32 v[30:31], v[66:67], v[66:67]
	v_pk_fma_f32 v[36:37], v[0:1], v[26:27], v[42:43] op_sel_hi:[0,1,1]
	v_pk_fma_f32 v[34:35], v[0:1], v[28:29], v[44:45] op_sel_hi:[0,1,1]
	v_pk_fma_f32 v[22:23], v[0:1], v[32:33], v[48:49] op_sel_hi:[0,1,1]
	v_pk_mul_f32 v[32:33], v[68:69], v[68:69]
	v_pk_fma_f32 v[28:29], v[0:1], v[2:3], v[50:51] op_sel_hi:[0,1,1]
	v_pk_fma_f32 v[26:27], v[0:1], v[4:5], v[52:53] op_sel_hi:[0,1,1]
	v_pk_fma_f32 v[20:21], v[0:1], v[6:7], v[54:55] op_sel_hi:[0,1,1]
	v_pk_fma_f32 v[18:19], v[0:1], v[8:9], v[56:57] op_sel_hi:[0,1,1]
	v_pk_fma_f32 v[8:9], v[0:1], v[10:11], v[58:59] op_sel_hi:[0,1,1]
	v_pk_fma_f32 v[6:7], v[0:1], v[12:13], v[60:61] op_sel_hi:[0,1,1]
	v_pk_fma_f32 v[4:5], v[0:1], v[14:15], v[62:63] op_sel_hi:[0,1,1]
	v_pk_fma_f32 v[2:3], v[0:1], v[16:17], v[64:65] op_sel_hi:[0,1,1]
	v_add_f32_e32 v0, v30, v31
	v_add_f32_e32 v0, v32, v0
	v_pk_mul_f32 v[40:41], v[70:71], v[70:71]
	v_add_f32_e32 v0, v33, v0
	v_add_f32_e32 v0, v40, v0
	v_pk_mul_f32 v[42:43], v[38:39], v[38:39]
	v_add_f32_e32 v0, v41, v0
	v_add_f32_e32 v0, v42, v0
	v_pk_mul_f32 v[44:45], v[36:37], v[36:37]
	v_add_f32_e32 v0, v43, v0
	v_add_f32_e32 v0, v44, v0
	v_pk_mul_f32 v[46:47], v[34:35], v[34:35]
	v_add_f32_e32 v0, v45, v0
	v_add_f32_e32 v0, v46, v0
	v_pk_mul_f32 v[48:49], v[24:25], v[24:25]
	v_add_f32_e32 v0, v47, v0
	v_add_f32_e32 v0, v48, v0
	v_pk_mul_f32 v[72:73], v[22:23], v[22:23]
	v_add_f32_e32 v0, v49, v0
	v_add_f32_e32 v0, v72, v0
	v_pk_mul_f32 v[50:51], v[28:29], v[28:29]
	v_add_f32_e32 v0, v73, v0
	v_add_f32_e32 v0, v50, v0
	v_pk_mul_f32 v[52:53], v[26:27], v[26:27]
	v_add_f32_e32 v0, v51, v0
	v_add_f32_e32 v0, v52, v0
	v_pk_mul_f32 v[54:55], v[20:21], v[20:21]
	v_add_f32_e32 v0, v53, v0
	v_add_f32_e32 v0, v54, v0
	v_pk_mul_f32 v[56:57], v[18:19], v[18:19]
	v_add_f32_e32 v0, v55, v0
	v_add_f32_e32 v0, v56, v0
	v_pk_mul_f32 v[10:11], v[8:9], v[8:9]
	v_add_f32_e32 v0, v57, v0
	v_add_f32_e32 v0, v10, v0
	v_pk_mul_f32 v[12:13], v[6:7], v[6:7]
	v_add_f32_e32 v0, v11, v0
	v_add_f32_e32 v0, v12, v0
	v_pk_mul_f32 v[14:15], v[4:5], v[4:5]
	v_add_f32_e32 v0, v13, v0
	v_add_f32_e32 v0, v14, v0
	v_pk_mul_f32 v[16:17], v[2:3], v[2:3]
	v_add_f32_e32 v0, v15, v0
	v_add_f32_e32 v0, v16, v0
	v_add_f32_e32 v0, v17, v0
	ds_bpermute_b32 v12, v234, v0
	v_bfi_b32 v10, s0, v191, v172
	v_lshl_add_u32 v11, v10, 2, v182
	s_and_saveexec_b64 s[0:1], vcc
	s_cbranch_execz .LBB0_871
	s_waitcnt lgkmcnt(0)
	v_add_f32_e32 v0, v0, v12
	ds_write_b32 v11, v0
	s_branch .LBB0_871
